# GU2 and D2: the units of the last partial round go to the first-arriving workgroups (ticket drawn one unit earlier, shared through LDS) instead of workgroups 0..rem-1
# baseline (speedup 1.0000x reference)
.LBB0_1688:
	s_add_i32 s42, s42, 1
	s_mul_i32 s4, s42, s46
	s_mul_hi_u32 s5, s42, s47
	s_add_i32 s5, s5, s4
	s_mul_i32 s4, s42, s47
	s_add_u32 s18, s4, s34
	s_addc_u32 s19, s5, s43
	s_cmp_lg_u32 s42, 6
	s_cbranch_scc1 .Ldl_h_gu2
	s_cmp_lg_u32 s94, 0x100
	s_cbranch_scc1 .Ldl_h_gu2
	v_mov_b32_e32 v236, 0x23fe0
	ds_read_b32 v237, v236
	s_waitcnt lgkmcnt(0)
	v_readfirstlane_b32 s18, v237
	s_nop 0
	s_add_u32 s18, s18, 0x600
	s_mov_b32 s19, 0
.Ldl_h_gu2:
	v_cmp_gt_i64_e32 vcc, s[18:19], v[144:145]
	v_cmp_lt_i64_e64 s[4:5], s[18:19], v[142:143]
	s_cbranch_vccnz .LBB0_1690
	s_mul_i32 s15, s19, 0x95fad40b
	s_mul_hi_u32 s16, s18, 0x95fad40b
	s_mul_hi_u32 s14, s19, 0x95fad40b
	s_add_u32 s15, s15, s16
	s_mul_i32 s13, s18, 0xa57eb502
	s_addc_u32 s14, s14, 0
	s_mul_hi_u32 s12, s18, 0xa57eb502
	s_add_u32 s13, s13, s15
	s_addc_u32 s12, s12, 0
	s_add_u32 s12, s14, s12
	s_addc_u32 s13, 0, 0
	s_mul_i32 s15, s19, 0xa57eb502
	s_mul_hi_u32 s14, s19, 0xa57eb502
	s_add_u32 s12, s15, s12
	s_addc_u32 s13, s14, s13
	s_ashr_i32 s14, s19, 31
	s_mul_i32 s15, s14, 0xa57eb502
	s_mul_hi_u32 s16, s14, 0x95fad40b
	s_add_i32 s15, s16, s15
	s_mul_i32 s14, s14, 0x95fad40b
	s_add_i32 s15, s15, s14
	s_sub_u32 s14, s14, s18
	s_subb_u32 s15, s15, s19
	s_add_u32 s12, s12, s14
	s_addc_u32 s13, s13, s15
	s_add_u32 s12, s12, s18
	s_addc_u32 s13, s13, s19
	s_ashr_i64 s[14:15], s[12:13], 10
	s_lshr_b32 s12, s13, 31
	s_add_u32 s12, s14, s12
	s_mul_i32 s13, s12, 0xfffff9d0
	s_add_i32 s13, s13, s18
	s_ashr_i32 s14, s13, 31
	s_lshr_b32 s14, s14, 29
	s_add_i32 s14, s13, s14
	s_ashr_i32 s15, s14, 3
	s_and_b32 s14, s14, -8
	s_sub_i32 s13, s13, s14
	s_cmp_lt_i32 s13, 0
	s_cselect_b32 s14, s39, 0xc6
	s_mul_i32 s13, s14, s13
	s_add_i32 s13, s13, s15
	s_mul_hi_i32 s14, s13, 0x2e8ba2e9
	s_lshr_b32 s15, s14, 31
	s_ashr_i32 s14, s14, 6
	s_add_i32 s14, s14, s15
	s_lshl_b32 s15, s14, 3
	s_sub_i32 s16, 36, s15
	s_min_i32 s16, s16, 8
	s_abs_i32 s17, s16
	v_cvt_f32_u32_e32 v0, s17
	s_sub_i32 s19, 0, s17
	s_mulk_i32 s14, 0x160
	s_sub_i32 s13, s13, s14
	v_rcp_iflag_f32_e32 v0, v0
	s_abs_i32 s18, s13
	s_xor_b32 s14, s13, s16
	s_ashr_i32 s14, s14, 31
	v_mul_f32_e32 v0, 0x4f7ffffe, v0
	v_cvt_u32_f32_e32 v0, v0
	s_nop 0
	v_readfirstlane_b32 s20, v0
	s_mul_i32 s19, s19, s20
	s_mul_hi_u32 s19, s20, s19
	s_add_i32 s20, s20, s19
	s_mul_hi_u32 s19, s18, s20
	s_mul_i32 s20, s19, s17
	s_sub_i32 s18, s18, s20
	s_add_i32 s20, s19, 1
	s_sub_i32 s21, s18, s17
	s_cmp_ge_u32 s18, s17
	s_cselect_b32 s19, s20, s19
	s_cselect_b32 s18, s21, s18
	s_add_i32 s20, s19, 1
	s_cmp_ge_u32 s18, s17
	s_cselect_b32 s17, s20, s19
	s_xor_b32 s17, s17, s14
	s_sub_i32 s14, s17, s14
	s_mul_i32 s16, s14, s16
	s_sub_i32 s13, s13, s16
	s_add_i32 s16, s13, s15

.LBB0_1694:
	v_mul_f32_e32 v158, 0xbfb8aa3b, v124
	v_mul_f32_e32 v159, 0xbfb8aa3b, v125
	v_exp_f32_e32 v158, v158
	v_exp_f32_e32 v159, v159
	v_mul_f32_e32 v160, 0xbfb8aa3b, v126
	v_mul_f32_e32 v161, 0xbfb8aa3b, v127
	v_exp_f32_e32 v160, v160
	v_exp_f32_e32 v161, v161
	v_add_f32_e32 v158, 1.0, v158
	v_add_f32_e32 v159, 1.0, v159
	v_rcp_f32_e32 v158, v158
	v_rcp_f32_e32 v159, v159
	v_add_f32_e32 v160, 1.0, v160
	v_add_f32_e32 v161, 1.0, v161
	v_rcp_f32_e32 v160, v160
	v_rcp_f32_e32 v161, v161
	v_pk_mul_f32 v[124:125], v[124:125], v[158:159]
	v_lshl_add_u32 v155, s24, 8, v129
	v_pk_mul_f32 v[120:121], v[124:125], v[120:121]
	v_pk_mul_f32 v[124:125], v[126:127], v[160:161]
	v_cvt_pk_bf16_f32 v120, v120, v121
	v_mul_f32_e32 v121, 0xbfb8aa3b, v116
	v_pk_mul_f32 v[122:123], v[124:125], v[122:123]
	v_exp_f32_e32 v124, v121
	v_mul_f32_e32 v121, 0xbfb8aa3b, v117
	v_exp_f32_e32 v125, v121
	v_cvt_pk_bf16_f32 v121, v122, v123
	v_add_f32_e32 v122, 1.0, v124
	v_mul_f32_e32 v124, 0xbfb8aa3b, v118
	v_add_f32_e32 v123, 1.0, v125
	v_mul_f32_e32 v125, 0xbfb8aa3b, v119
	v_exp_f32_e32 v124, v124
	v_exp_f32_e32 v125, v125
	v_rcp_f32_e32 v122, v122
	v_rcp_f32_e32 v123, v123
	v_add_f32_e32 v124, 1.0, v124
	v_add_f32_e32 v125, 1.0, v125
	v_rcp_f32_e32 v124, v124
	v_rcp_f32_e32 v125, v125
	v_pk_mul_f32 v[116:117], v[116:117], v[122:123]
	v_lshl_or_b32 v146, s22, 7, v151
	v_pk_mul_f32 v[112:113], v[116:117], v[112:113]
	v_mul_f32_e32 v116, 0xbfb8aa3b, v110
	v_cvt_pk_bf16_f32 v122, v112, v113
	v_pk_mul_f32 v[112:113], v[118:119], v[124:125]
	v_mul_f32_e32 v117, 0xbfb8aa3b, v111
	v_pk_mul_f32 v[112:113], v[112:113], v[114:115]
	v_mul_f32_e32 v114, 0xbfb8aa3b, v108
	v_mul_f32_e32 v115, 0xbfb8aa3b, v109
	v_exp_f32_e32 v114, v114
	v_exp_f32_e32 v115, v115
	v_exp_f32_e32 v116, v116
	v_exp_f32_e32 v117, v117
	v_add_f32_e32 v114, 1.0, v114
	v_add_f32_e32 v115, 1.0, v115
	v_rcp_f32_e32 v114, v114
	v_rcp_f32_e32 v115, v115
	v_add_f32_e32 v116, 1.0, v116
	v_add_f32_e32 v117, 1.0, v117
	v_rcp_f32_e32 v116, v116
	v_rcp_f32_e32 v117, v117
	v_pk_mul_f32 v[108:109], v[108:109], v[114:115]
	v_ashrrev_i32_e32 v147, 31, v146
	v_pk_mul_f32 v[104:105], v[108:109], v[104:105]
	v_pk_mul_f32 v[108:109], v[110:111], v[116:117]
	v_cvt_pk_bf16_f32 v104, v104, v105
	v_mul_f32_e32 v105, 0xbfb8aa3b, v100
	v_pk_mul_f32 v[106:107], v[108:109], v[106:107]
	v_exp_f32_e32 v108, v105
	v_mul_f32_e32 v105, 0xbfb8aa3b, v101
	v_exp_f32_e32 v109, v105
	v_cvt_pk_bf16_f32 v105, v106, v107
	v_add_f32_e32 v106, 1.0, v108
	v_mul_f32_e32 v108, 0xbfb8aa3b, v102
	v_add_f32_e32 v107, 1.0, v109
	v_mul_f32_e32 v109, 0xbfb8aa3b, v103
	v_exp_f32_e32 v108, v108
	v_exp_f32_e32 v109, v109
	v_rcp_f32_e32 v106, v106
	v_rcp_f32_e32 v107, v107
	v_add_f32_e32 v108, 1.0, v108
	v_add_f32_e32 v109, 1.0, v109
	v_rcp_f32_e32 v108, v108
	v_rcp_f32_e32 v109, v109
	v_pk_mul_f32 v[100:101], v[100:101], v[106:107]
	v_mov_b64_e32 v[148:149], s[6:7]
	v_pk_mul_f32 v[96:97], v[100:101], v[96:97]
	v_mul_f32_e32 v100, 0xbfb8aa3b, v94
	v_cvt_pk_bf16_f32 v106, v96, v97
	v_pk_mul_f32 v[96:97], v[102:103], v[108:109]
	v_mul_f32_e32 v101, 0xbfb8aa3b, v95
	v_pk_mul_f32 v[96:97], v[96:97], v[98:99]
	v_mul_f32_e32 v98, 0xbfb8aa3b, v92
	v_mul_f32_e32 v99, 0xbfb8aa3b, v93
	v_exp_f32_e32 v98, v98
	v_exp_f32_e32 v99, v99
	v_exp_f32_e32 v100, v100
	v_exp_f32_e32 v101, v101
	v_add_f32_e32 v98, 1.0, v98
	v_add_f32_e32 v99, 1.0, v99
	v_rcp_f32_e32 v98, v98
	v_rcp_f32_e32 v99, v99
	v_add_f32_e32 v100, 1.0, v100
	v_add_f32_e32 v101, 1.0, v101
	v_rcp_f32_e32 v100, v100
	v_rcp_f32_e32 v101, v101
	v_pk_mul_f32 v[92:93], v[92:93], v[98:99]
	v_cvt_pk_bf16_f32 v123, v112, v113
	v_pk_mul_f32 v[88:89], v[92:93], v[88:89]
	v_pk_mul_f32 v[92:93], v[94:95], v[100:101]
	v_cvt_pk_bf16_f32 v88, v88, v89
	v_mul_f32_e32 v89, 0xbfb8aa3b, v84
	v_pk_mul_f32 v[90:91], v[92:93], v[90:91]
	v_exp_f32_e32 v92, v89
	v_mul_f32_e32 v89, 0xbfb8aa3b, v85
	v_exp_f32_e32 v93, v89
	v_cvt_pk_bf16_f32 v89, v90, v91
	v_add_f32_e32 v90, 1.0, v92
	v_mul_f32_e32 v92, 0xbfb8aa3b, v86
	v_add_f32_e32 v91, 1.0, v93
	v_mul_f32_e32 v93, 0xbfb8aa3b, v87
	v_exp_f32_e32 v92, v92
	v_exp_f32_e32 v93, v93
	v_rcp_f32_e32 v90, v90
	v_rcp_f32_e32 v91, v91
	v_add_f32_e32 v92, 1.0, v92
	v_add_f32_e32 v93, 1.0, v93
	v_rcp_f32_e32 v92, v92
	v_rcp_f32_e32 v93, v93
	v_pk_mul_f32 v[84:85], v[84:85], v[90:91]
	v_or_b32_e32 v112, 16, v155
	v_pk_mul_f32 v[80:81], v[84:85], v[80:81]
	v_mul_f32_e32 v84, 0xbfb8aa3b, v78
	v_cvt_pk_bf16_f32 v90, v80, v81
	v_pk_mul_f32 v[80:81], v[86:87], v[92:93]
	v_mul_f32_e32 v85, 0xbfb8aa3b, v79
	v_pk_mul_f32 v[80:81], v[80:81], v[82:83]
	v_mul_f32_e32 v82, 0xbfb8aa3b, v76
	v_mul_f32_e32 v83, 0xbfb8aa3b, v77
	v_exp_f32_e32 v82, v82
	v_exp_f32_e32 v83, v83
	v_exp_f32_e32 v84, v84
	v_exp_f32_e32 v85, v85
	v_add_f32_e32 v82, 1.0, v82
	v_add_f32_e32 v83, 1.0, v83
	v_rcp_f32_e32 v82, v82
	v_rcp_f32_e32 v83, v83
	v_add_f32_e32 v84, 1.0, v84
	v_add_f32_e32 v85, 1.0, v85
	v_rcp_f32_e32 v84, v84
	v_rcp_f32_e32 v85, v85
	v_pk_mul_f32 v[76:77], v[76:77], v[82:83]
	v_cvt_pk_bf16_f32 v107, v96, v97
	v_pk_mul_f32 v[72:73], v[76:77], v[72:73]
	v_pk_mul_f32 v[76:77], v[78:79], v[84:85]
	v_cvt_pk_bf16_f32 v72, v72, v73
	v_mul_f32_e32 v73, 0xbfb8aa3b, v68
	v_pk_mul_f32 v[74:75], v[76:77], v[74:75]
	v_exp_f32_e32 v76, v73
	v_mul_f32_e32 v73, 0xbfb8aa3b, v69
	v_exp_f32_e32 v77, v73
	v_cvt_pk_bf16_f32 v73, v74, v75
	v_add_f32_e32 v74, 1.0, v76
	v_mul_f32_e32 v76, 0xbfb8aa3b, v70
	v_add_f32_e32 v75, 1.0, v77
	v_mul_f32_e32 v77, 0xbfb8aa3b, v71
	v_exp_f32_e32 v76, v76
	v_exp_f32_e32 v77, v77
	v_rcp_f32_e32 v74, v74
	v_rcp_f32_e32 v75, v75
	v_add_f32_e32 v76, 1.0, v76
	v_add_f32_e32 v77, 1.0, v77
	v_rcp_f32_e32 v76, v76
	v_rcp_f32_e32 v77, v77
	v_pk_mul_f32 v[68:69], v[68:69], v[74:75]
	v_or_b32_e32 v96, 32, v155
	v_pk_mul_f32 v[64:65], v[68:69], v[64:65]
	v_mul_f32_e32 v68, 0xbfb8aa3b, v62
	v_cvt_pk_bf16_f32 v74, v64, v65
	v_pk_mul_f32 v[64:65], v[70:71], v[76:77]
	v_mul_f32_e32 v69, 0xbfb8aa3b, v63
	v_pk_mul_f32 v[64:65], v[64:65], v[66:67]
	v_mul_f32_e32 v66, 0xbfb8aa3b, v60
	v_mul_f32_e32 v67, 0xbfb8aa3b, v61
	v_exp_f32_e32 v66, v66
	v_exp_f32_e32 v67, v67
	v_exp_f32_e32 v68, v68
	v_exp_f32_e32 v69, v69
	v_add_f32_e32 v66, 1.0, v66
	v_add_f32_e32 v67, 1.0, v67
	v_rcp_f32_e32 v66, v66
	v_rcp_f32_e32 v67, v67
	v_add_f32_e32 v68, 1.0, v68
	v_add_f32_e32 v69, 1.0, v69
	v_rcp_f32_e32 v68, v68
	v_rcp_f32_e32 v69, v69
	v_pk_mul_f32 v[60:61], v[60:61], v[66:67]
	v_cvt_pk_bf16_f32 v91, v80, v81
	v_pk_mul_f32 v[56:57], v[60:61], v[56:57]
	v_pk_mul_f32 v[60:61], v[62:63], v[68:69]
	v_cvt_pk_bf16_f32 v56, v56, v57
	v_mul_f32_e32 v57, 0xbfb8aa3b, v52
	v_pk_mul_f32 v[58:59], v[60:61], v[58:59]
	v_exp_f32_e32 v60, v57
	v_mul_f32_e32 v57, 0xbfb8aa3b, v53
	v_exp_f32_e32 v61, v57
	v_cvt_pk_bf16_f32 v57, v58, v59
	v_add_f32_e32 v58, 1.0, v60
	v_mul_f32_e32 v60, 0xbfb8aa3b, v54
	v_add_f32_e32 v59, 1.0, v61
	v_mul_f32_e32 v61, 0xbfb8aa3b, v55
	v_exp_f32_e32 v60, v60
	v_exp_f32_e32 v61, v61
	v_rcp_f32_e32 v58, v58
	v_rcp_f32_e32 v59, v59
	v_add_f32_e32 v60, 1.0, v60
	v_add_f32_e32 v61, 1.0, v61
	v_rcp_f32_e32 v60, v60
	v_rcp_f32_e32 v61, v61
	v_pk_mul_f32 v[52:53], v[52:53], v[58:59]
	v_or_b32_e32 v80, 48, v155
	v_pk_mul_f32 v[48:49], v[52:53], v[48:49]
	v_mul_f32_e32 v52, 0xbfb8aa3b, v46
	v_cvt_pk_bf16_f32 v58, v48, v49
	v_pk_mul_f32 v[48:49], v[54:55], v[60:61]
	v_mul_f32_e32 v53, 0xbfb8aa3b, v47
	v_pk_mul_f32 v[48:49], v[48:49], v[50:51]
	v_mul_f32_e32 v50, 0xbfb8aa3b, v44
	v_mul_f32_e32 v51, 0xbfb8aa3b, v45
	v_exp_f32_e32 v50, v50
	v_exp_f32_e32 v51, v51
	v_exp_f32_e32 v52, v52
	v_exp_f32_e32 v53, v53
	v_add_f32_e32 v50, 1.0, v50
	v_add_f32_e32 v51, 1.0, v51
	v_rcp_f32_e32 v50, v50
	v_rcp_f32_e32 v51, v51
	v_add_f32_e32 v52, 1.0, v52
	v_add_f32_e32 v53, 1.0, v53
	v_rcp_f32_e32 v52, v52
	v_rcp_f32_e32 v53, v53
	v_pk_mul_f32 v[44:45], v[44:45], v[50:51]
	v_cvt_pk_bf16_f32 v75, v64, v65
	v_pk_mul_f32 v[40:41], v[44:45], v[40:41]
	v_pk_mul_f32 v[44:45], v[46:47], v[52:53]
	v_cvt_pk_bf16_f32 v40, v40, v41
	v_mul_f32_e32 v41, 0xbfb8aa3b, v36
	v_pk_mul_f32 v[42:43], v[44:45], v[42:43]
	v_exp_f32_e32 v44, v41
	v_mul_f32_e32 v41, 0xbfb8aa3b, v37
	v_exp_f32_e32 v45, v41
	v_cvt_pk_bf16_f32 v41, v42, v43
	v_add_f32_e32 v42, 1.0, v44
	v_mul_f32_e32 v44, 0xbfb8aa3b, v38
	v_add_f32_e32 v43, 1.0, v45
	v_mul_f32_e32 v45, 0xbfb8aa3b, v39
	v_exp_f32_e32 v44, v44
	v_exp_f32_e32 v45, v45
	v_rcp_f32_e32 v42, v42
	v_rcp_f32_e32 v43, v43
	v_add_f32_e32 v44, 1.0, v44
	v_add_f32_e32 v45, 1.0, v45
	v_rcp_f32_e32 v44, v44
	v_rcp_f32_e32 v45, v45
	v_pk_mul_f32 v[36:37], v[36:37], v[42:43]
	v_add_u32_e32 v64, 0x80, v155
	v_pk_mul_f32 v[32:33], v[36:37], v[32:33]
	v_mul_f32_e32 v36, 0xbfb8aa3b, v30
	v_cvt_pk_bf16_f32 v42, v32, v33
	v_pk_mul_f32 v[32:33], v[38:39], v[44:45]
	v_mul_f32_e32 v37, 0xbfb8aa3b, v31
	v_pk_mul_f32 v[32:33], v[32:33], v[34:35]
	v_mul_f32_e32 v34, 0xbfb8aa3b, v28
	v_mul_f32_e32 v35, 0xbfb8aa3b, v29
	v_exp_f32_e32 v34, v34
	v_exp_f32_e32 v35, v35
	v_exp_f32_e32 v36, v36
	v_exp_f32_e32 v37, v37
	v_add_f32_e32 v34, 1.0, v34
	v_add_f32_e32 v35, 1.0, v35
	v_rcp_f32_e32 v34, v34
	v_rcp_f32_e32 v35, v35
	v_add_f32_e32 v36, 1.0, v36
	v_add_f32_e32 v37, 1.0, v37
	v_rcp_f32_e32 v36, v36
	v_rcp_f32_e32 v37, v37
	v_pk_mul_f32 v[28:29], v[28:29], v[34:35]
	v_cvt_pk_bf16_f32 v59, v48, v49
	v_pk_mul_f32 v[24:25], v[28:29], v[24:25]
	v_pk_mul_f32 v[28:29], v[30:31], v[36:37]
	v_cvt_pk_bf16_f32 v24, v24, v25
	v_mul_f32_e32 v25, 0xbfb8aa3b, v20
	v_pk_mul_f32 v[26:27], v[28:29], v[26:27]
	v_exp_f32_e32 v28, v25
	v_mul_f32_e32 v25, 0xbfb8aa3b, v21
	v_exp_f32_e32 v29, v25
	v_cvt_pk_bf16_f32 v25, v26, v27
	v_add_f32_e32 v26, 1.0, v28
	v_mul_f32_e32 v28, 0xbfb8aa3b, v22
	v_add_f32_e32 v27, 1.0, v29
	v_mul_f32_e32 v29, 0xbfb8aa3b, v23
	v_exp_f32_e32 v28, v28
	v_exp_f32_e32 v29, v29
	v_rcp_f32_e32 v26, v26
	v_rcp_f32_e32 v27, v27
	v_add_f32_e32 v28, 1.0, v28
	v_add_f32_e32 v29, 1.0, v29
	v_rcp_f32_e32 v28, v28
	v_rcp_f32_e32 v29, v29
	v_pk_mul_f32 v[20:21], v[20:21], v[26:27]
	v_add_u32_e32 v48, 0x90, v155
	v_pk_mul_f32 v[16:17], v[20:21], v[16:17]
	v_mul_f32_e32 v20, 0xbfb8aa3b, v14
	v_cvt_pk_bf16_f32 v26, v16, v17
	v_pk_mul_f32 v[16:17], v[22:23], v[28:29]
	v_mul_f32_e32 v21, 0xbfb8aa3b, v15
	v_pk_mul_f32 v[16:17], v[16:17], v[18:19]
	v_mul_f32_e32 v18, 0xbfb8aa3b, v12
	v_mul_f32_e32 v19, 0xbfb8aa3b, v13
	v_exp_f32_e32 v18, v18
	v_exp_f32_e32 v19, v19
	v_exp_f32_e32 v20, v20
	v_exp_f32_e32 v21, v21
	v_add_f32_e32 v18, 1.0, v18
	v_add_f32_e32 v19, 1.0, v19
	v_rcp_f32_e32 v18, v18
	v_rcp_f32_e32 v19, v19
	v_add_f32_e32 v20, 1.0, v20
	v_add_f32_e32 v21, 1.0, v21
	v_rcp_f32_e32 v20, v20
	v_rcp_f32_e32 v21, v21
	v_pk_mul_f32 v[12:13], v[12:13], v[18:19]
	v_cvt_pk_bf16_f32 v43, v32, v33
	v_pk_mul_f32 v[8:9], v[12:13], v[8:9]
	v_pk_mul_f32 v[12:13], v[14:15], v[20:21]
	v_cvt_pk_bf16_f32 v8, v8, v9
	v_mul_f32_e32 v9, 0xbfb8aa3b, v4
	v_pk_mul_f32 v[10:11], v[12:13], v[10:11]
	v_exp_f32_e32 v12, v9
	v_mul_f32_e32 v9, 0xbfb8aa3b, v5
	v_exp_f32_e32 v13, v9
	v_cvt_pk_bf16_f32 v9, v10, v11
	v_add_f32_e32 v10, 1.0, v12
	v_mul_f32_e32 v12, 0xbfb8aa3b, v6
	v_add_f32_e32 v11, 1.0, v13
	v_mul_f32_e32 v13, 0xbfb8aa3b, v7
	v_exp_f32_e32 v12, v12
	v_exp_f32_e32 v13, v13
	v_rcp_f32_e32 v10, v10
	v_rcp_f32_e32 v11, v11
	v_add_f32_e32 v12, 1.0, v12
	v_add_f32_e32 v13, 1.0, v13
	v_rcp_f32_e32 v12, v12
	v_rcp_f32_e32 v13, v13
	v_pk_mul_f32 v[4:5], v[4:5], v[10:11]
	v_add_u32_e32 v32, 0xa0, v155
	v_pk_mul_f32 v[0:1], v[4:5], v[0:1]
	v_cvt_pk_bf16_f32 v27, v16, v17
	v_add_u32_e32 v16, 0xb0, v155
	v_cvt_pk_bf16_f32 v10, v0, v1
	v_pk_mul_f32 v[0:1], v[6:7], v[12:13]
	v_mad_i64_i32 v[156:157], s[26:27], v155, s54, v[148:149]
	v_lshlrev_b64 v[146:147], 1, v[146:147]
	v_mad_i64_i32 v[112:113], s[26:27], v112, s54, v[148:149]
	v_mad_i64_i32 v[96:97], s[26:27], v96, s54, v[148:149]
	v_mad_i64_i32 v[80:81], s[26:27], v80, s54, v[148:149]
	v_mad_i64_i32 v[64:65], s[26:27], v64, s54, v[148:149]
	v_mad_i64_i32 v[48:49], s[26:27], v48, s54, v[148:149]
	v_mad_i64_i32 v[32:33], s[26:27], v32, s54, v[148:149]
	v_mad_i64_i32 v[16:17], s[26:27], v16, s54, v[148:149]
	v_pk_mul_f32 v[0:1], v[0:1], v[2:3]
	v_lshl_add_u64 v[156:157], v[156:157], 0, v[146:147]
	v_lshl_add_u64 v[112:113], v[112:113], 0, v[146:147]
	v_lshl_add_u64 v[96:97], v[96:97], 0, v[146:147]
	v_lshl_add_u64 v[80:81], v[80:81], 0, v[146:147]
	v_lshl_add_u64 v[64:65], v[64:65], 0, v[146:147]
	v_lshl_add_u64 v[48:49], v[48:49], 0, v[146:147]
	v_lshl_add_u64 v[32:33], v[32:33], 0, v[146:147]
	v_lshl_add_u64 v[16:17], v[16:17], 0, v[146:147]
	v_cvt_pk_bf16_f32 v11, v0, v1
	s_andn2_b64 vcc, exec, s[4:5]
	s_mov_b64 s[4:5], -1
	global_store_dwordx4 v[156:157], v[120:123], off
	v_and_b32_e32 v254, 63, v128
	v_and_b32_e32 v255, 3, v254
	v_lshrrev_b32_e32 v254, 2, v254
	v_lshl_or_b32 v254, v255, 4, v254
	v_lshlrev_b32_e32 v254, 2, v254
	ds_bpermute_b32 v238, v254, v104
	ds_bpermute_b32 v239, v254, v105
	ds_bpermute_b32 v240, v254, v106
	ds_bpermute_b32 v241, v254, v107
	ds_bpermute_b32 v236, v254, v112
	ds_bpermute_b32 v237, v254, v113
	ds_bpermute_b32 v244, v254, v88
	ds_bpermute_b32 v245, v254, v89
	ds_bpermute_b32 v246, v254, v90
	ds_bpermute_b32 v247, v254, v91
	ds_bpermute_b32 v242, v254, v96
	ds_bpermute_b32 v243, v254, v97
	ds_bpermute_b32 v250, v254, v72
	ds_bpermute_b32 v251, v254, v73
	ds_bpermute_b32 v252, v254, v74
	ds_bpermute_b32 v253, v254, v75
	ds_bpermute_b32 v248, v254, v80
	ds_bpermute_b32 v249, v254, v81
	s_waitcnt lgkmcnt(12)
	global_store_dwordx4 v[236:237], v[238:241], off
	s_nop 0
	ds_bpermute_b32 v238, v254, v56
	ds_bpermute_b32 v239, v254, v57
	ds_bpermute_b32 v240, v254, v58
	ds_bpermute_b32 v241, v254, v59
	ds_bpermute_b32 v236, v254, v64
	ds_bpermute_b32 v237, v254, v65
	s_waitcnt lgkmcnt(12)
	global_store_dwordx4 v[242:243], v[244:247], off
	s_nop 0
	ds_bpermute_b32 v244, v254, v40
	ds_bpermute_b32 v245, v254, v41
	ds_bpermute_b32 v246, v254, v42
	ds_bpermute_b32 v247, v254, v43
	ds_bpermute_b32 v242, v254, v48
	ds_bpermute_b32 v243, v254, v49
	s_waitcnt lgkmcnt(12)
	global_store_dwordx4 v[248:249], v[250:253], off
	s_nop 0
	ds_bpermute_b32 v250, v254, v24
	ds_bpermute_b32 v251, v254, v25
	ds_bpermute_b32 v252, v254, v26
	ds_bpermute_b32 v253, v254, v27
	ds_bpermute_b32 v248, v254, v32
	ds_bpermute_b32 v249, v254, v33
	s_waitcnt lgkmcnt(12)
	global_store_dwordx4 v[236:237], v[238:241], off
	s_nop 0
	ds_bpermute_b32 v238, v254, v8
	ds_bpermute_b32 v239, v254, v9
	ds_bpermute_b32 v240, v254, v10
	ds_bpermute_b32 v241, v254, v11
	ds_bpermute_b32 v236, v254, v16
	ds_bpermute_b32 v237, v254, v17
	s_waitcnt lgkmcnt(12)
	global_store_dwordx4 v[242:243], v[244:247], off
	s_waitcnt lgkmcnt(6)
	global_store_dwordx4 v[248:249], v[250:253], off
	s_waitcnt lgkmcnt(0)
	global_store_dwordx4 v[236:237], v[238:241], off
	s_cmp_lg_u32 s42, 5
	s_cbranch_scc1 .Ldl_skip_gu2
	s_cmp_lg_u32 s94, 0x100
	s_cbranch_scc1 .Ldl_skip_gu2
	s_mov_b64 s[82:83], exec
	v_readlane_b32 s84, v235, 17
	v_readlane_b32 s85, v235, 18
	s_nop 0
	s_and_b64 s[84:85], s[82:83], s[84:85]
	s_mov_b64 exec, s[84:85]
	s_cbranch_execz .Ldl_done_gu2
	v_mov_b32_e32 v236, 0x1480
	v_mov_b32_e32 v237, 1
	global_atomic_add v237, v236, v237, s[50:51] sc0
	v_mov_b32_e32 v236, 0x23fe0
	s_waitcnt vmcnt(0)
	ds_write_b32 v236, v237
	s_waitcnt lgkmcnt(0)
.Ldl_done_gu2:
	s_mov_b64 exec, s[82:83]
	s_barrier
.Ldl_skip_gu2:
	s_cbranch_vccnz .LBB0_1687
	s_andn2_b64 vcc, exec, s[2:3]
	s_cbranch_vccnz .LBB0_1686
	s_barrier
	s_branch .LBB0_1686

.LBB0_1759:
	s_add_i32 s41, s41, 1
	s_mul_i32 s4, s41, s45
	s_mul_hi_u32 s5, s41, s46
	s_add_i32 s5, s5, s4
	s_mul_i32 s4, s41, s46
	s_add_u32 s4, s4, s34
	s_addc_u32 s5, s5, s42
	s_cmp_lg_u32 s41, 4
	s_cbranch_scc1 .Ldl_h_d2
	s_cmp_lg_u32 s94, 0x100
	s_cbranch_scc1 .Ldl_h_d2
	v_mov_b32_e32 v236, 0x23fe0
	ds_read_b32 v237, v236
	s_waitcnt lgkmcnt(0)
	v_readfirstlane_b32 s4, v237
	s_nop 0
	s_add_u32 s4, s4, 0x400
	s_mov_b32 s5, 0
.Ldl_h_d2:
	v_cmp_gt_i64_e32 vcc, s[4:5], v[144:145]
	v_cmp_lt_i64_e64 s[6:7], s[4:5], v[142:143]
	s_cbranch_vccnz .LBB0_1761
	s_mul_i32 s27, s5, 0x38e38e39
	s_mul_hi_u32 s28, s4, 0x38e38e39
	s_mul_hi_u32 s26, s5, 0x38e38e39
	s_add_u32 s27, s27, s28
	s_mul_i32 s21, s4, 0xe38e38e
	s_addc_u32 s26, s26, 0
	s_mul_hi_u32 s20, s4, 0xe38e38e
	s_add_u32 s21, s21, s27
	s_addc_u32 s20, s20, 0
	s_add_u32 s20, s26, s20
	s_addc_u32 s21, 0, 0
	s_mul_i32 s27, s5, 0xe38e38e
	s_mul_hi_u32 s26, s5, 0xe38e38e
	s_add_u32 s20, s27, s20
	s_addc_u32 s21, s26, s21
	s_ashr_i32 s5, s5, 31
	s_mul_i32 s26, s5, 0xe38e38e
	s_mul_hi_u32 s27, s5, 0x38e38e39
	s_add_i32 s26, s27, s26
	s_mul_i32 s5, s5, 0x38e38e39
	s_add_i32 s26, s26, s5
	s_add_u32 s20, s20, s5
	s_addc_u32 s21, s21, s26
	s_lshr_b32 s5, s21, 31
	s_lshr_b64 s[20:21], s[20:21], 4
	s_add_i32 s60, s20, s5
	s_mul_i32 s5, s60, 0xfffffee0
	s_add_i32 s4, s5, s4
	s_ashr_i32 s5, s4, 31
	s_lshr_b32 s5, s5, 29
	s_add_i32 s5, s4, s5
	s_ashr_i32 s20, s5, 3
	s_and_b32 s5, s5, -8
	s_sub_i32 s4, s4, s5
	s_cmp_lt_i32 s4, 0
	s_cselect_b32 s5, 37, 36
	s_mul_i32 s4, s5, s4
	s_add_i32 s4, s4, s20
	s_ashr_i32 s5, s4, 31
	s_lshr_b32 s5, s5, 26
	s_add_i32 s5, s4, s5
	s_ashr_i32 s20, s5, 6
	s_lshl_b32 s20, s20, 3
	s_sub_i32 s21, 36, s20
	s_min_i32 s21, s21, 8
	s_abs_i32 s26, s21
	v_cvt_f32_u32_e32 v0, s26
	s_sub_i32 s28, 0, s26
	s_andn2_b32 s5, s5, 63
	s_sub_i32 s4, s4, s5
	v_rcp_iflag_f32_e32 v0, v0
	s_abs_i32 s27, s4
	s_xor_b32 s5, s4, s21
	s_ashr_i32 s5, s5, 31
	v_mul_f32_e32 v0, 0x4f7ffffe, v0
	v_cvt_u32_f32_e32 v0, v0
	s_nop 0
	v_readfirstlane_b32 s29, v0
	s_mul_i32 s28, s28, s29
	s_mul_hi_u32 s28, s29, s28
	s_add_i32 s29, s29, s28
	s_mul_hi_u32 s28, s27, s29
	s_mul_i32 s29, s28, s26
	s_sub_i32 s27, s27, s29
	s_add_i32 s29, s28, 1
	s_sub_i32 s62, s27, s26
	s_cmp_ge_u32 s27, s26
	s_cselect_b32 s28, s29, s28
	s_cselect_b32 s27, s62, s27
	s_add_i32 s29, s28, 1
	s_cmp_ge_u32 s27, s26
	s_cselect_b32 s26, s29, s28
	s_xor_b32 s26, s26, s5
	s_sub_i32 s62, s26, s5
	s_mul_i32 s5, s62, s21
	s_sub_i32 s4, s4, s5
	s_add_i32 s63, s4, s20

.LBB0_1769:
	v_and_b32_e32 v254, 63, v128
	v_and_b32_e32 v255, 3, v254
	v_lshrrev_b32_e32 v254, 2, v254
	v_lshl_or_b32 v254, v255, 4, v254
	v_lshlrev_b32_e32 v254, 2, v254
	s_cmp_lt_i32 s47, 2
	s_cselect_b32 s22, s54, 0x1aa05000
	s_add_u32 s22, s50, s22
	s_addc_u32 s23, s51, 0
	s_bitcmp1_b32 s47, 0
	s_cselect_b32 s24, 0x2400000, 0
	s_add_u32 s22, s22, s24
	v_lshl_or_b32 v152, s59, 8, v147
	v_lshl_add_u32 v154, s61, 8, v129
	s_addc_u32 s23, s23, 0
	v_ashrrev_i32_e32 v153, 31, v152
	v_ashrrev_i32_e32 v155, 31, v154
	v_lshl_add_u64 v[152:153], v[152:153], 1, s[22:23]
	v_lshlrev_b64 v[156:157], 12, v[154:155]
	v_lshl_add_u64 v[156:157], v[152:153], 0, v[156:157]
	v_cvt_pk_bf16_f32 v60, v60, v61
	v_cvt_pk_bf16_f32 v61, v62, v63
	v_cvt_pk_bf16_f32 v62, v56, v57
	v_add_co_u32_e32 v56, vcc, s55, v156
	v_cvt_pk_bf16_f32 v68, v68, v69
	v_cvt_pk_bf16_f32 v69, v70, v71
	v_cvt_pk_bf16_f32 v70, v64, v65
	v_lshl_add_u64 v[64:65], v[156:157], 0, s[12:13]
	v_addc_co_u32_e32 v57, vcc, 0, v157, vcc
	v_cvt_pk_bf16_f32 v44, v44, v45
	v_cvt_pk_bf16_f32 v45, v46, v47
	v_cvt_pk_bf16_f32 v46, v40, v41
	v_cvt_pk_bf16_f32 v47, v42, v43
	ds_bpermute_b32 v238, v254, v44
	ds_bpermute_b32 v239, v254, v45
	ds_bpermute_b32 v240, v254, v46
	ds_bpermute_b32 v241, v254, v47
	ds_bpermute_b32 v236, v254, v64
	ds_bpermute_b32 v237, v254, v65
	v_cvt_pk_bf16_f32 v108, v108, v109
	v_cvt_pk_bf16_f32 v109, v110, v111
	v_add_co_u32_e32 v46, vcc, s56, v156
	v_cvt_pk_bf16_f32 v110, v104, v105
	v_or_b32_e32 v104, 16, v154
	v_lshl_add_u64 v[44:45], v[156:157], 0, s[14:15]
	v_addc_co_u32_e32 v47, vcc, 0, v157, vcc
	v_cvt_pk_bf16_f32 v28, v28, v29
	v_cvt_pk_bf16_f32 v29, v30, v31
	v_cvt_pk_bf16_f32 v30, v24, v25
	v_cvt_pk_bf16_f32 v31, v26, v27
	v_ashrrev_i32_e32 v105, 31, v104
	v_cvt_pk_bf16_f32 v92, v92, v93
	v_cvt_pk_bf16_f32 v93, v94, v95
	v_cvt_pk_bf16_f32 v94, v88, v89
	v_or_b32_e32 v88, 32, v154
	ds_bpermute_b32 v244, v254, v28
	ds_bpermute_b32 v245, v254, v29
	ds_bpermute_b32 v246, v254, v30
	ds_bpermute_b32 v247, v254, v31
	ds_bpermute_b32 v242, v254, v44
	ds_bpermute_b32 v243, v254, v45
	v_cvt_pk_bf16_f32 v111, v106, v107
	v_lshlrev_b64 v[104:105], 12, v[104:105]
	v_add_co_u32_e32 v30, vcc, s57, v156
	v_ashrrev_i32_e32 v89, 31, v88
	v_cvt_pk_bf16_f32 v76, v76, v77
	v_cvt_pk_bf16_f32 v77, v78, v79
	v_cvt_pk_bf16_f32 v78, v72, v73
	v_or_b32_e32 v72, 48, v154
	v_lshl_add_u64 v[28:29], v[156:157], 0, s[16:17]
	v_addc_co_u32_e32 v31, vcc, 0, v157, vcc
	v_cvt_pk_bf16_f32 v12, v12, v13
	v_cvt_pk_bf16_f32 v13, v14, v15
	v_cvt_pk_bf16_f32 v14, v8, v9
	v_cvt_pk_bf16_f32 v15, v10, v11
	ds_bpermute_b32 v250, v254, v108
	ds_bpermute_b32 v251, v254, v109
	ds_bpermute_b32 v252, v254, v110
	ds_bpermute_b32 v253, v254, v111
	ds_bpermute_b32 v248, v254, v156
	ds_bpermute_b32 v249, v254, v157
	v_cvt_pk_bf16_f32 v95, v90, v91
	v_lshlrev_b64 v[88:89], 12, v[88:89]
	v_lshl_add_u64 v[108:109], v[152:153], 0, v[104:105]
	v_ashrrev_i32_e32 v73, 31, v72
	s_waitcnt lgkmcnt(12)
	global_store_dwordx4 v[236:237], v[238:241], off offset:256
	s_nop 0
	ds_bpermute_b32 v238, v254, v12
	ds_bpermute_b32 v239, v254, v13
	ds_bpermute_b32 v240, v254, v14
	ds_bpermute_b32 v241, v254, v15
	ds_bpermute_b32 v236, v254, v28
	ds_bpermute_b32 v237, v254, v29
	s_waitcnt lgkmcnt(12)
	global_store_dwordx4 v[242:243], v[244:247], off offset:256
	s_nop 0
	ds_bpermute_b32 v244, v254, v92
	ds_bpermute_b32 v245, v254, v93
	ds_bpermute_b32 v246, v254, v94
	ds_bpermute_b32 v247, v254, v95
	ds_bpermute_b32 v242, v254, v108
	ds_bpermute_b32 v243, v254, v109
	v_cvt_pk_bf16_f32 v79, v74, v75
	v_add_co_u32_e32 v14, vcc, s58, v156
	v_lshl_add_u64 v[92:93], v[152:153], 0, v[88:89]
	v_lshlrev_b64 v[72:73], 12, v[72:73]
	v_addc_co_u32_e32 v15, vcc, 0, v157, vcc
	v_cvt_pk_bf16_f32 v124, v124, v125
	v_cvt_pk_bf16_f32 v125, v126, v127
	v_cvt_pk_bf16_f32 v126, v120, v121
	v_cvt_pk_bf16_f32 v127, v122, v123
	v_cvt_pk_bf16_f32 v104, v116, v117
	v_cvt_pk_bf16_f32 v105, v118, v119
	v_cvt_pk_bf16_f32 v106, v112, v113
	v_cvt_pk_bf16_f32 v107, v114, v115
	v_cvt_pk_bf16_f32 v88, v100, v101
	v_cvt_pk_bf16_f32 v89, v102, v103
	v_cvt_pk_bf16_f32 v90, v96, v97
	v_cvt_pk_bf16_f32 v91, v98, v99
	s_waitcnt lgkmcnt(12)
	global_store_dwordx4 v[248:249], v[250:253], off offset:256
	s_nop 0
	ds_bpermute_b32 v250, v254, v76
	ds_bpermute_b32 v251, v254, v77
	ds_bpermute_b32 v252, v254, v78
	ds_bpermute_b32 v253, v254, v79
	ds_bpermute_b32 v248, v254, v92
	ds_bpermute_b32 v249, v254, v93
	v_cvt_pk_bf16_f32 v74, v80, v81
	v_cvt_pk_bf16_f32 v75, v82, v83
	v_lshl_add_u64 v[76:77], v[152:153], 0, v[72:73]
	v_cvt_pk_bf16_f32 v72, v84, v85
	v_cvt_pk_bf16_f32 v73, v86, v87
	v_cvt_pk_bf16_f32 v71, v66, v67
	v_cvt_pk_bf16_f32 v63, v58, v59
	v_cvt_pk_bf16_f32 v40, v52, v53
	v_cvt_pk_bf16_f32 v41, v54, v55
	v_cvt_pk_bf16_f32 v42, v48, v49
	v_cvt_pk_bf16_f32 v43, v50, v51
	v_cvt_pk_bf16_f32 v24, v36, v37
	v_cvt_pk_bf16_f32 v25, v38, v39
	v_cvt_pk_bf16_f32 v26, v32, v33
	v_cvt_pk_bf16_f32 v27, v34, v35
	v_lshl_add_u64 v[12:13], v[156:157], 0, s[18:19]
	v_cvt_pk_bf16_f32 v8, v20, v21
	v_cvt_pk_bf16_f32 v9, v22, v23
	v_cvt_pk_bf16_f32 v10, v16, v17
	v_cvt_pk_bf16_f32 v11, v18, v19
	v_cvt_pk_bf16_f32 v4, v4, v5
	v_cvt_pk_bf16_f32 v5, v6, v7
	v_cvt_pk_bf16_f32 v6, v0, v1
	v_cvt_pk_bf16_f32 v7, v2, v3
	s_and_b64 vcc, exec, s[4:5]
	s_mov_b64 s[4:5], -1
	s_waitcnt lgkmcnt(12)
	global_store_dwordx4 v[236:237], v[238:241], off offset:256
	s_nop 0
	ds_bpermute_b32 v238, v254, v124
	ds_bpermute_b32 v239, v254, v125
	ds_bpermute_b32 v240, v254, v126
	ds_bpermute_b32 v241, v254, v127
	ds_bpermute_b32 v236, v254, v156
	ds_bpermute_b32 v237, v254, v157
	s_waitcnt lgkmcnt(12)
	global_store_dwordx4 v[242:243], v[244:247], off offset:256
	s_nop 0
	ds_bpermute_b32 v244, v254, v104
	ds_bpermute_b32 v245, v254, v105
	ds_bpermute_b32 v246, v254, v106
	ds_bpermute_b32 v247, v254, v107
	ds_bpermute_b32 v242, v254, v108
	ds_bpermute_b32 v243, v254, v109
	s_waitcnt lgkmcnt(12)
	global_store_dwordx4 v[248:249], v[250:253], off offset:256
	s_nop 0
	ds_bpermute_b32 v250, v254, v88
	ds_bpermute_b32 v251, v254, v89
	ds_bpermute_b32 v252, v254, v90
	ds_bpermute_b32 v253, v254, v91
	ds_bpermute_b32 v248, v254, v92
	ds_bpermute_b32 v249, v254, v93
	s_waitcnt lgkmcnt(12)
	global_store_dwordx4 v[236:237], v[238:241], off
	s_nop 0
	ds_bpermute_b32 v238, v254, v72
	ds_bpermute_b32 v239, v254, v73
	ds_bpermute_b32 v240, v254, v74
	ds_bpermute_b32 v241, v254, v75
	ds_bpermute_b32 v236, v254, v76
	ds_bpermute_b32 v237, v254, v77
	s_waitcnt lgkmcnt(12)
	global_store_dwordx4 v[242:243], v[244:247], off
	s_nop 0
	ds_bpermute_b32 v244, v254, v68
	ds_bpermute_b32 v245, v254, v69
	ds_bpermute_b32 v246, v254, v70
	ds_bpermute_b32 v247, v254, v71
	ds_bpermute_b32 v242, v254, v76
	ds_bpermute_b32 v243, v254, v77
	s_waitcnt lgkmcnt(12)
	global_store_dwordx4 v[248:249], v[250:253], off
	s_nop 0
	ds_bpermute_b32 v250, v254, v60
	ds_bpermute_b32 v251, v254, v61
	ds_bpermute_b32 v252, v254, v62
	ds_bpermute_b32 v253, v254, v63
	ds_bpermute_b32 v248, v254, v56
	ds_bpermute_b32 v249, v254, v57
	s_waitcnt lgkmcnt(12)
	global_store_dwordx4 v[236:237], v[238:241], off
	s_nop 0
	ds_bpermute_b32 v238, v254, v40
	ds_bpermute_b32 v239, v254, v41
	ds_bpermute_b32 v240, v254, v42
	ds_bpermute_b32 v241, v254, v43
	ds_bpermute_b32 v236, v254, v46
	ds_bpermute_b32 v237, v254, v47
	s_waitcnt lgkmcnt(12)
	global_store_dwordx4 v[242:243], v[244:247], off offset:256
	s_nop 0
	ds_bpermute_b32 v244, v254, v24
	ds_bpermute_b32 v245, v254, v25
	ds_bpermute_b32 v246, v254, v26
	ds_bpermute_b32 v247, v254, v27
	ds_bpermute_b32 v242, v254, v30
	ds_bpermute_b32 v243, v254, v31
	s_waitcnt lgkmcnt(12)
	global_store_dwordx4 v[248:249], v[250:253], off
	s_nop 0
	ds_bpermute_b32 v250, v254, v8
	ds_bpermute_b32 v251, v254, v9
	ds_bpermute_b32 v252, v254, v10
	ds_bpermute_b32 v253, v254, v11
	ds_bpermute_b32 v248, v254, v14
	ds_bpermute_b32 v249, v254, v15
	s_waitcnt lgkmcnt(12)
	global_store_dwordx4 v[236:237], v[238:241], off
	s_nop 0
	ds_bpermute_b32 v238, v254, v4
	ds_bpermute_b32 v239, v254, v5
	ds_bpermute_b32 v240, v254, v6
	ds_bpermute_b32 v241, v254, v7
	ds_bpermute_b32 v236, v254, v12
	ds_bpermute_b32 v237, v254, v13
	s_waitcnt lgkmcnt(12)
	global_store_dwordx4 v[242:243], v[244:247], off
	s_waitcnt lgkmcnt(6)
	global_store_dwordx4 v[248:249], v[250:253], off
	s_waitcnt lgkmcnt(0)
	global_store_dwordx4 v[236:237], v[238:241], off offset:256
	s_cmp_lg_u32 s41, 3
	s_cbranch_scc1 .Ldl_skip_d2
	s_cmp_lg_u32 s94, 0x100
	s_cbranch_scc1 .Ldl_skip_d2
	s_mov_b64 s[82:83], exec
	v_readlane_b32 s84, v235, 17
	v_readlane_b32 s85, v235, 18
	s_nop 0
	s_and_b64 s[84:85], s[82:83], s[84:85]
	s_mov_b64 exec, s[84:85]
	s_cbranch_execz .Ldl_done_d2
	v_mov_b32_e32 v236, 0x1580
	v_mov_b32_e32 v237, 1
	global_atomic_add v237, v236, v237, s[50:51] sc0
	v_mov_b32_e32 v236, 0x23fe0
	s_waitcnt vmcnt(0)
	ds_write_b32 v236, v237
	s_waitcnt lgkmcnt(0)

.Ldl_skip_d2:
	s_cbranch_vccnz .LBB0_1758
	s_andn2_b64 vcc, exec, s[0:1]
	s_cbranch_vccnz .LBB0_1757
	s_barrier
	s_branch .LBB0_1757
